# v35: v34 plus running output-row pointer in the two GLA chunk store blocks (1 address add per store instead of 5-6 VALU)
# speedup vs baseline: 1.0112x; 1.0073x over previous
.LBB0_969:
	v_mov_b32_e32 v86, v159
	s_waitcnt lgkmcnt(0)
	s_barrier
	v_cvt_pk_bf16_f32 v194, v58, v59
	v_and_b32_e32 v84, 31, v86
	v_bfe_u32 v192, v86, 5, 1
	v_lshlrev_b32_e32 v87, 4, v86
	v_lshlrev_b32_e32 v200, 4, v192
	v_lshlrev_b32_e32 v193, 8, v84
	v_and_b32_e32 v201, 0x70, v87
	v_bitop3_b32 v66, v201, v193, v200 bitop3:0xde
	v_add_u32_e32 v70, 0, v66
	ds_read_b128 v[66:69], v70 offset:8192
	ds_read_b128 v[70:73], v70
	s_waitcnt lgkmcnt(0)
	v_mfma_f32_32x32x16_bf16 v[68:83], v[66:69], v[70:73], 0
	v_or_b32_e32 v66, 32, v200
	v_bitop3_b32 v66, v66, v193, v201 bitop3:0xde
	v_add_u32_e32 v66, 0, v66
	ds_read_b128 v[140:143], v66 offset:8192
	ds_read_b128 v[144:147], v66
	v_or_b32_e32 v66, 64, v200
	v_bitop3_b32 v66, v66, v193, v201 bitop3:0xde
	v_add_u32_e32 v66, 0, v66
	s_waitcnt lgkmcnt(0)
	v_mfma_f32_32x32x16_bf16 v[68:83], v[140:143], v[144:147], v[68:83]
	ds_read_b128 v[140:143], v66 offset:8192
	ds_read_b128 v[144:147], v66
	v_or_b32_e32 v66, 0x60, v200
	v_bitop3_b32 v66, v66, v193, v201 bitop3:0xde
	v_add_u32_e32 v66, 0, v66
	ds_read_b128 v[148:151], v66 offset:8192
	v_and_b32_e32 v67, 63, v86
	v_lshlrev_b32_e32 v86, 1, v86
	s_waitcnt lgkmcnt(0)
	v_mfma_f32_32x32x16_bf16 v[68:83], v[140:143], v[144:147], v[68:83]
	ds_read_b128 v[140:143], v66
	v_or_b32_e32 v66, 0x80, v200
	v_bitop3_b32 v66, v66, v193, v201 bitop3:0xde
	v_add_u32_e32 v66, 0, v66
	ds_read_b128 v[144:147], v66 offset:8192
	v_lshlrev_b32_e32 v67, 3, v67
	v_and_b32_e32 v87, 0xc0, v87
	s_waitcnt lgkmcnt(0)
	v_mfma_f32_32x32x16_bf16 v[68:83], v[148:151], v[140:143], v[68:83]
	ds_read_b128 v[140:143], v66
	v_or_b32_e32 v66, 0xa0, v200
	v_bitop3_b32 v66, v66, v193, v201 bitop3:0xde
	v_add_u32_e32 v66, 0, v66
	ds_read_b128 v[148:151], v66 offset:8192
	v_and_b32_e32 v152, 32, v86
	v_lshlrev_b32_e32 v86, 2, v192
	s_waitcnt lgkmcnt(0)
	v_mfma_f32_32x32x16_bf16 v[68:83], v[144:147], v[140:143], v[68:83]
	ds_read_b128 v[140:143], v66
	v_or_b32_e32 v66, 0xc0, v200
	v_bitop3_b32 v66, v66, v193, v201 bitop3:0xde
	v_add_u32_e32 v66, 0, v66
	ds_read_b128 v[144:147], v66 offset:8192
	v_and_b32_e32 v153, 0x100, v67
	v_and_or_b32 v67, v67, 24, v87
	s_waitcnt lgkmcnt(0)
	v_mfma_f32_32x32x16_bf16 v[68:83], v[148:151], v[140:143], v[68:83]
	ds_read_b128 v[140:143], v66
	v_or_b32_e32 v66, 0xe0, v200
	v_bitop3_b32 v66, v66, v193, v201 bitop3:0xde
	v_add_u32_e32 v66, 0, v66
	ds_read_b128 v[148:151], v66 offset:8192
	v_cmp_le_u32_e32 vcc, v86, v84
	v_or3_b32 v204, v67, v152, v153
	s_waitcnt lgkmcnt(0)
	v_mfma_f32_32x32x16_bf16 v[68:83], v[144:147], v[140:143], v[68:83]
	ds_read_b128 v[140:143], v66
	v_or_b32_e32 v191, 2, v86
	v_or_b32_e32 v190, 3, v86
	v_or_b32_e32 v189, 8, v86
	v_or_b32_e32 v188, 9, v86
	v_or_b32_e32 v187, 10, v86
	v_lshlrev_b32_e32 v203, 3, v192
	s_waitcnt lgkmcnt(0)
	v_mfma_f32_32x32x16_bf16 v[68:83], v[148:151], v[140:143], v[68:83]
	v_add_u32_e32 v205, 0, v193
	v_or_b32_e32 v186, 11, v86
	v_or_b32_e32 v185, 16, v86
	v_or_b32_e32 v184, 17, v86
	v_or_b32_e32 v183, 18, v86
	v_or_b32_e32 v182, 19, v86
	v_or_b32_e32 v181, 24, v86
	s_nop 4
	v_cvt_pk_bf16_f32 v66, v68, s0
	v_cndmask_b32_e32 v66, 0, v66, vcc
	v_cvt_pk_bf16_f32 v67, v69, s0
	v_cmp_lt_u32_e32 vcc, v86, v84
	v_add3_u32 v69, v205, v201, v203
	ds_read2_b64 v[142:145], v69 offset1:16
	v_cndmask_b32_e32 v67, 0, v67, vcc
	v_perm_b32 v152, v67, v66, s45
	v_cvt_pk_bf16_f32 v66, v70, s0
	v_cmp_le_u32_e32 vcc, v191, v84
	v_cvt_pk_bf16_f32 v67, v71, s0
	v_or_b32_e32 v70, 16, v203
	v_cndmask_b32_e32 v66, 0, v66, vcc
	v_cmp_le_u32_e32 vcc, v190, v84
	v_xad_u32 v70, v70, v201, v205
	s_waitcnt lgkmcnt(0)
	v_mov_b32_e32 v71, v143
	v_cndmask_b32_e32 v67, 0, v67, vcc
	v_perm_b32 v153, v67, v66, s45
	v_cvt_pk_bf16_f32 v66, v72, s0
	v_cmp_le_u32_e32 vcc, v189, v84
	v_cvt_pk_bf16_f32 v67, v73, s0
	ds_read_b64 v[72:73], v70
	v_cndmask_b32_e32 v66, 0, v66, vcc
	v_cmp_le_u32_e32 vcc, v188, v84
	v_mov_b32_e32 v70, v142
	v_cvt_pk_bf16_f32 v68, v54, v55
	v_cndmask_b32_e32 v67, 0, v67, vcc
	v_perm_b32 v154, v67, v66, s45
	v_cvt_pk_bf16_f32 v66, v74, s0
	v_cmp_le_u32_e32 vcc, v187, v84
	v_cvt_pk_bf16_f32 v67, v75, s0
	v_or_b32_e32 v74, 32, v203
	v_cndmask_b32_e32 v66, 0, v66, vcc
	v_cmp_le_u32_e32 vcc, v186, v84
	v_or_b32_e32 v75, 48, v203
	v_cvt_pk_bf16_f32 v69, v56, v57
	v_cndmask_b32_e32 v67, 0, v67, vcc
	v_perm_b32 v155, v67, v66, s45
	v_cvt_pk_bf16_f32 v66, v76, s0
	v_cmp_le_u32_e32 vcc, v185, v84
	v_cvt_pk_bf16_f32 v67, v77, s0
	v_or_b32_e32 v76, 64, v203
	v_cndmask_b32_e32 v66, 0, v66, vcc
	v_cmp_le_u32_e32 vcc, v184, v84
	v_xad_u32 v74, v74, v201, v205
	v_xad_u32 v75, v75, v201, v205
	v_cndmask_b32_e32 v67, 0, v67, vcc
	v_perm_b32 v140, v67, v66, s45
	v_cvt_pk_bf16_f32 v66, v78, s0
	v_cmp_le_u32_e32 vcc, v183, v84
	v_cvt_pk_bf16_f32 v67, v79, s0
	v_xad_u32 v76, v76, v201, v205
	v_cndmask_b32_e32 v66, 0, v66, vcc
	v_cmp_le_u32_e32 vcc, v182, v84
	v_cvt_pk_bf16_f32 v151, v81, s0
	ds_read_b64 v[146:147], v74
	ds_read_b64 v[148:149], v75
	ds_read_b64 v[192:193], v76
	v_cndmask_b32_e32 v67, 0, v67, vcc
	v_perm_b32 v141, v67, v66, s45
	v_cvt_pk_bf16_f32 v66, v80, s0
	v_cmp_le_u32_e32 vcc, v181, v84
	v_cvt_pk_bf16_f32 v67, v52, v53
	v_or_b32_e32 v143, 0x50, v203
	v_cndmask_b32_e32 v150, 0, v66, vcc
	v_cvt_pk_bf16_f32 v66, v50, v51
	v_cvt_pk_bf16_f32 v195, v60, v61
	v_cvt_pk_bf16_f32 v196, v62, v63
	s_waitcnt lgkmcnt(0)
	v_mfma_f32_32x32x16_bf16 v[66:81], v[70:73], v[66:69], 0
	v_cvt_pk_bf16_f32 v197, v64, v65
	v_xad_u32 v143, v143, v201, v205
	v_or_b32_e32 v167, 25, v86
	v_cmp_le_u32_e32 vcc, v167, v84
	v_or_b32_e32 v163, 26, v86
	v_or_b32_e32 v87, 27, v86
	v_cndmask_b32_e32 v142, 0, v151, vcc
	v_mfma_f32_32x32x16_bf16 v[66:81], v[146:149], v[194:197], v[66:81]
	ds_read_b64 v[194:195], v143
	v_cvt_pk_bf16_f32 v146, v34, v35
	v_cvt_pk_bf16_f32 v147, v36, v37
	v_cvt_pk_bf16_f32 v148, v38, v39
	v_cvt_pk_bf16_f32 v149, v40, v41
	v_perm_b32 v142, v142, v150, s45
	v_or_b32_e32 v143, 0x60, v203
	s_waitcnt lgkmcnt(0)
	v_mfma_f32_32x32x16_bf16 v[66:81], v[192:195], v[146:149], v[66:81]
	v_or_b32_e32 v150, 0x70, v203
	v_or_b32_e32 v151, 0x90, v203
	v_xad_u32 v143, v143, v201, v205
	v_xad_u32 v150, v150, v201, v205
	v_xad_u32 v151, v151, v201, v205
	ds_read_b64 v[196:197], v143
	ds_read_b64 v[198:199], v150
	ds_read_b64 v[150:151], v151
	v_cvt_pk_bf16_f32 v146, v42, v43
	v_cvt_pk_bf16_f32 v147, v44, v45
	v_cvt_pk_bf16_f32 v148, v46, v47
	v_cvt_pk_bf16_f32 v149, v48, v49
	v_or_b32_e32 v143, 0xa0, v203
	v_xad_u32 v143, v143, v201, v205
	s_waitcnt lgkmcnt(0)
	v_mfma_f32_32x32x16_bf16 v[66:81], v[196:199], v[146:149], v[66:81]
	v_mov_b32_e32 v148, v144
	v_mov_b32_e32 v149, v145
	v_cvt_pk_bf16_f32 v144, v18, v19
	v_cvt_pk_bf16_f32 v145, v20, v21
	v_cvt_pk_bf16_f32 v146, v22, v23
	v_cvt_pk_bf16_f32 v147, v24, v25
	v_or_b32_e32 v192, 0xd0, v203
	v_xad_u32 v194, v192, v201, v205
	v_mfma_f32_32x32x16_bf16 v[66:81], v[148:151], v[144:147], v[66:81]
	v_or_b32_e32 v146, 0xb0, v203
	v_xad_u32 v146, v146, v201, v205
	ds_read_b64 v[148:149], v143
	ds_read_b64 v[150:151], v146
	v_cvt_pk_bf16_f32 v144, v26, v27
	v_cvt_pk_bf16_f32 v145, v28, v29
	v_cvt_pk_bf16_f32 v146, v30, v31
	v_cvt_pk_bf16_f32 v147, v32, v33
	v_or_b32_e32 v143, 0xc0, v203
	v_xad_u32 v143, v143, v201, v205
	s_waitcnt lgkmcnt(0)
	v_mfma_f32_32x32x16_bf16 v[66:81], v[148:151], v[144:147], v[66:81]
	ds_read_b64 v[192:193], v143
	ds_read_b64 v[194:195], v194
	v_cvt_pk_bf16_f32 v82, v82, s0
	v_cmp_le_u32_e32 vcc, v163, v84
	v_cvt_pk_bf16_f32 v83, v83, s0
	v_cvt_pk_bf16_f32 v144, v2, v3
	v_cndmask_b32_e32 v82, 0, v82, vcc
	v_cmp_le_u32_e32 vcc, v87, v84
	v_cvt_pk_bf16_f32 v145, v4, v5
	v_cvt_pk_bf16_f32 v146, v6, v7
	v_cvt_pk_bf16_f32 v147, v8, v9
	v_cndmask_b32_e32 v83, 0, v83, vcc
	v_perm_b32 v143, v83, v82, s45
	s_waitcnt lgkmcnt(0)
	v_mfma_f32_32x32x16_bf16 v[66:81], v[192:195], v[144:147], v[66:81]
	v_or_b32_e32 v82, 0xe0, v203
	v_xad_u32 v82, v82, v201, v205
	v_or_b32_e32 v83, 0xf0, v203
	v_xad_u32 v83, v83, v201, v205
	ds_read_b64 v[144:145], v82
	ds_read_b64 v[146:147], v83
	v_cvt_pk_bf16_f32 v148, v10, v11
	v_cvt_pk_bf16_f32 v149, v12, v13
	v_cvt_pk_bf16_f32 v150, v14, v15
	v_cvt_pk_bf16_f32 v151, v16, v17
	v_add_u32_e32 v202, s7, v204
	s_add_i32 s14, s20, -2
	s_waitcnt lgkmcnt(0)
	v_mfma_f32_32x32x16_bf16 v[66:81], v[144:147], v[148:151], v[66:81]
	ds_read_b64_tr_b16 v[144:145], v202 offset:0
	ds_read_b64_tr_b16 v[146:147], v202 offset:0x800
	ds_read_b64_tr_b16 v[148:149], v202 offset:0x1000
	ds_read_b64_tr_b16 v[150:151], v202 offset:0x1800
	s_waitcnt lgkmcnt(0)
	v_permlane32_swap_b32_e32 v152, v154
	v_permlane32_swap_b32_e32 v153, v155
	v_permlane32_swap_b32_e32 v140, v142
	v_permlane32_swap_b32_e32 v141, v143
	v_add_u32_e32 v82, 0, v200
	v_add_u32_e32 v83, 0x14400, v82
	v_mfma_f32_32x32x16_bf16 v[66:81], v[152:155], v[144:147], v[66:81]
	ds_read_b128 v[152:155], v83
	v_add_u32_e32 v83, 0x14420, v82
	ds_read_b128 v[192:195], v83
	v_add_u32_e32 v83, 0x14440, v82
	ds_read_b128 v[196:199], v83
	v_add_u32_e32 v83, 0x14460, v82
	ds_read_b128 v[200:203], v83
	s_waitcnt lgkmcnt(0)
	v_pk_mul_f32 v[50:51], v[50:51], v[152:153]
	v_add_u32_e32 v83, s51, v204
	ds_read_b64_tr_b16 v[152:153], v83 offset:0
	v_pk_mul_f32 v[52:53], v[52:53], v[154:155]
	ds_read_b64_tr_b16 v[154:155], v83 offset:0x800
	v_pk_mul_f32 v[54:55], v[54:55], v[192:193]
	ds_read_b64_tr_b16 v[192:193], v83 offset:0x1000
	v_pk_mul_f32 v[56:57], v[56:57], v[194:195]
	ds_read_b64_tr_b16 v[194:195], v83 offset:0x1800
	s_waitcnt lgkmcnt(0)
	v_pk_mul_f32 v[62:63], v[62:63], v[200:201]
	v_pk_mul_f32 v[58:59], v[58:59], v[196:197]
	v_pk_mul_f32 v[64:65], v[64:65], v[202:203]
	v_pk_mul_f32 v[60:61], v[60:61], v[198:199]
	s_nop 1
	v_mfma_f32_32x32x16_bf16 v[50:65], v[152:155], v[144:147], v[50:65]
	v_add_u32_e32 v152, 0x14480, v82
	ds_read_b128 v[152:155], v152
	v_add_u32_e32 v196, 0x144c0, v82
	v_add_u32_e32 v200, 0x144e0, v82
	ds_read_b128 v[196:199], v196
	ds_read_b128 v[200:203], v200
	s_waitcnt lgkmcnt(0)
	v_pk_mul_f32 v[42:43], v[42:43], v[196:197]
	v_mfma_f32_32x32x16_bf16 v[50:65], v[192:195], v[148:151], v[50:65]
	v_add_u32_e32 v192, 0x144a0, v82
	ds_read_b128 v[192:195], v192
	v_mul_f32_e64 v34, v34, v152
	v_mul_f32_e64 v35, v35, v153
	ds_read_b64_tr_b16 v[152:153], v83 offset:0x200
	v_mul_f32_e64 v36, v36, v154
	v_mul_f32_e64 v37, v37, v155
	ds_read_b64_tr_b16 v[154:155], v83 offset:0xa00
	s_waitcnt lgkmcnt(0)
	v_pk_mul_f32 v[38:39], v[38:39], v[192:193]
	ds_read_b64_tr_b16 v[192:193], v83 offset:0x1200
	v_pk_mul_f32 v[40:41], v[40:41], v[194:195]
	ds_read_b64_tr_b16 v[194:195], v83 offset:0x1a00
	s_waitcnt lgkmcnt(0)
	v_pk_mul_f32 v[46:47], v[46:47], v[200:201]
	v_pk_mul_f32 v[48:49], v[48:49], v[202:203]
	v_pk_mul_f32 v[44:45], v[44:45], v[198:199]
	s_nop 1
	v_mfma_f32_32x32x16_bf16 v[34:49], v[152:155], v[144:147], v[34:49]
	v_add_u32_e32 v152, 0x14500, v82
	ds_read_b128 v[152:155], v152
	v_add_u32_e32 v196, 0x14540, v82
	v_add_u32_e32 v200, 0x14560, v82
	ds_read_b128 v[196:199], v196
	ds_read_b128 v[200:203], v200
	s_waitcnt lgkmcnt(0)
	v_pk_mul_f32 v[26:27], v[26:27], v[196:197]
	v_mfma_f32_32x32x16_bf16 v[34:49], v[192:195], v[148:151], v[34:49]
	v_add_u32_e32 v192, 0x14520, v82
	ds_read_b128 v[192:195], v192
	v_mul_f32_e64 v18, v18, v152
	v_mul_f32_e64 v19, v19, v153
	ds_read_b64_tr_b16 v[152:153], v83 offset:0x400
	v_mul_f32_e64 v20, v20, v154
	v_mul_f32_e64 v21, v21, v155
	ds_read_b64_tr_b16 v[154:155], v83 offset:0xc00
	s_waitcnt lgkmcnt(0)
	v_pk_mul_f32 v[22:23], v[22:23], v[192:193]
	ds_read_b64_tr_b16 v[192:193], v83 offset:0x1400
	v_pk_mul_f32 v[24:25], v[24:25], v[194:195]
	ds_read_b64_tr_b16 v[194:195], v83 offset:0x1c00
	s_waitcnt lgkmcnt(0)
	v_pk_mul_f32 v[30:31], v[30:31], v[200:201]
	v_pk_mul_f32 v[32:33], v[32:33], v[202:203]
	v_pk_mul_f32 v[28:29], v[28:29], v[198:199]
	s_nop 1
	v_mfma_f32_32x32x16_bf16 v[18:33], v[152:155], v[144:147], v[18:33]
	v_add_u32_e32 v152, 0x14580, v82
	ds_read_b128 v[152:155], v152
	v_add_u32_e32 v196, 0x145c0, v82
	ds_read_b128 v[196:199], v196
	s_waitcnt lgkmcnt(0)
	v_pk_mul_f32 v[10:11], v[10:11], v[196:197]
	v_mfma_f32_32x32x16_bf16 v[18:33], v[192:195], v[148:151], v[18:33]
	v_add_u32_e32 v192, 0x145a0, v82
	v_add_u32_e32 v82, 0x145e0, v82
	ds_read_b128 v[192:195], v192
	ds_read_b128 v[200:203], v82
	v_mul_f32_e64 v2, v2, v152
	v_mul_f32_e64 v3, v3, v153
	v_pk_mul_f32 v[4:5], v[4:5], v[154:155]
	v_pk_mul_f32 v[12:13], v[12:13], v[198:199]
	v_mfma_f32_32x32x16_bf16 v[66:81], v[140:143], v[148:151], v[66:81]
	ds_read_b64_tr_b16 v[140:141], v83 offset:0x600
	ds_read_b64_tr_b16 v[142:143], v83 offset:0xe00
	ds_read_b64_tr_b16 v[152:153], v83 offset:0x1600
	ds_read_b64_tr_b16 v[154:155], v83 offset:0x1e00
	s_waitcnt lgkmcnt(0)
	s_waitcnt lgkmcnt(0)
	v_mul_f32_e64 v14, v14, v200
	v_mul_f32_e64 v15, v15, v201
	v_mul_f32_e64 v6, v6, v192
	v_mul_f32_e64 v7, v7, v193
	v_pk_mul_f32 v[16:17], v[16:17], v[202:203]
	v_pk_mul_f32 v[8:9], v[8:9], v[194:195]
	s_add_i32 s15, s48, -1
	s_cmp_lg_u64 s[12:13], 0
	s_movk_i32 s100, 0x800
	s_cselect_b32 s100, s100, 0xfffff800
	s_cselect_b32 s101, 0, -1
	s_movk_i32 s98, 0x2800
	s_cselect_b32 s98, s98, 0xffffd800
	s_cselect_b32 s99, 0, -1
	s_and_b64 s[0:1], s[12:13], exec
	s_cselect_b32 s0, s14, s15
	v_lshlrev_b32_e32 v84, 1, v84
	s_lshl_b32 s0, s0, 5
	v_lshl_add_u64 v[82:83], s[28:29], 0, v[84:85]
	v_xor_b32_e32 v84, 31, v86
	s_add_i32 s0, s0, s47
	v_cndmask_b32_e64 v84, v84, v86, s[12:13]
	v_or_b32_e32 v84, s0, v84
	v_lshlrev_b32_e32 v84, 11, v84
	v_mfma_f32_32x32x16_bf16 v[2:17], v[140:143], v[144:147], v[2:17]
	v_cvt_pk_bf16_f32 v66, v66, s0
	v_lshl_add_u64 v[250:251], v[82:83], 0, v[84:85]
	global_store_short v[250:251], v66, off
	v_cvt_pk_bf16_f32 v140, v67, s0
	v_lshl_add_u64 v[250:251], v[250:251], 0, s[100:101]
	global_store_short v[250:251], v140, off
	v_cvt_pk_bf16_f32 v68, v68, s0
	v_lshl_add_u64 v[250:251], v[250:251], 0, s[100:101]
	global_store_short v[250:251], v68, off
	v_cvt_pk_bf16_f32 v68, v69, s0
	v_lshl_add_u64 v[250:251], v[250:251], 0, s[100:101]
	global_store_short v[250:251], v68, off
	v_cvt_pk_bf16_f32 v68, v70, s0
	v_lshl_add_u64 v[250:251], v[250:251], 0, s[98:99]
	global_store_short v[250:251], v68, off
	v_cvt_pk_bf16_f32 v68, v71, s0
	v_lshl_add_u64 v[250:251], v[250:251], 0, s[100:101]
	global_store_short v[250:251], v68, off
	v_cvt_pk_bf16_f32 v68, v72, s0
	v_lshl_add_u64 v[250:251], v[250:251], 0, s[100:101]
	global_store_short v[250:251], v68, off
	v_cvt_pk_bf16_f32 v68, v73, s0
	v_lshl_add_u64 v[250:251], v[250:251], 0, s[100:101]
	global_store_short v[250:251], v68, off
	v_cvt_pk_bf16_f32 v68, v74, s0
	v_lshl_add_u64 v[250:251], v[250:251], 0, s[98:99]
	global_store_short v[250:251], v68, off
	v_cvt_pk_bf16_f32 v68, v75, s0
	v_lshl_add_u64 v[250:251], v[250:251], 0, s[100:101]
	global_store_short v[250:251], v68, off
	v_cvt_pk_bf16_f32 v68, v76, s0
	v_lshl_add_u64 v[250:251], v[250:251], 0, s[100:101]
	global_store_short v[250:251], v68, off
	v_cvt_pk_bf16_f32 v68, v77, s0
	v_lshl_add_u64 v[250:251], v[250:251], 0, s[100:101]
	global_store_short v[250:251], v68, off
	v_cvt_pk_bf16_f32 v68, v78, s0
	v_lshl_add_u64 v[250:251], v[250:251], 0, s[98:99]
	global_store_short v[250:251], v68, off
	v_cvt_pk_bf16_f32 v68, v79, s0
	v_lshl_add_u64 v[250:251], v[250:251], 0, s[100:101]
	global_store_short v[250:251], v68, off
	v_mfma_f32_32x32x16_bf16 v[2:17], v[152:155], v[148:151], v[2:17]
	v_cvt_pk_bf16_f32 v68, v80, s0
	v_lshl_add_u64 v[250:251], v[250:251], 0, s[100:101]
	global_store_short v[250:251], v68, off
	s_add_i32 s20, s20, 2
	s_add_i32 s48, s48, -2
	v_cvt_pk_bf16_f32 v68, v81, s0
	s_cmp_gt_u32 s49, 61
	v_lshl_add_u64 v[250:251], v[250:251], 0, s[100:101]
	global_store_short v[250:251], v68, off
	s_cbranch_scc1 .LBB0_960

.LBB0_977:
	v_mov_b32_e32 v86, v159
	s_waitcnt lgkmcnt(0)
	s_barrier
	v_cvt_pk_bf16_f32 v194, v58, v59
	v_and_b32_e32 v84, 31, v86
	v_bfe_u32 v192, v86, 5, 1
	v_lshlrev_b32_e32 v87, 4, v86
	v_lshlrev_b32_e32 v200, 4, v192
	v_lshlrev_b32_e32 v193, 8, v84
	v_and_b32_e32 v201, 0x70, v87
	v_bitop3_b32 v66, v201, v193, v200 bitop3:0xde
	v_add_u32_e32 v70, 0, v66
	ds_read_b128 v[66:69], v70 offset:8192
	ds_read_b128 v[70:73], v70
	s_waitcnt lgkmcnt(0)
	v_mfma_f32_32x32x16_bf16 v[68:83], v[66:69], v[70:73], 0
	v_or_b32_e32 v66, 32, v200
	v_bitop3_b32 v66, v66, v193, v201 bitop3:0xde
	v_add_u32_e32 v66, 0, v66
	ds_read_b128 v[140:143], v66 offset:8192
	ds_read_b128 v[144:147], v66
	v_or_b32_e32 v66, 64, v200
	v_bitop3_b32 v66, v66, v193, v201 bitop3:0xde
	v_add_u32_e32 v66, 0, v66
	s_waitcnt lgkmcnt(0)
	v_mfma_f32_32x32x16_bf16 v[68:83], v[140:143], v[144:147], v[68:83]
	ds_read_b128 v[140:143], v66 offset:8192
	ds_read_b128 v[144:147], v66
	v_or_b32_e32 v66, 0x60, v200
	v_bitop3_b32 v66, v66, v193, v201 bitop3:0xde
	v_add_u32_e32 v66, 0, v66
	ds_read_b128 v[148:151], v66 offset:8192
	v_and_b32_e32 v67, 63, v86
	v_lshlrev_b32_e32 v67, 3, v67
	s_waitcnt lgkmcnt(0)
	v_mfma_f32_32x32x16_bf16 v[68:83], v[140:143], v[144:147], v[68:83]
	ds_read_b128 v[140:143], v66
	v_or_b32_e32 v66, 0x80, v200
	v_bitop3_b32 v66, v66, v193, v201 bitop3:0xde
	v_add_u32_e32 v66, 0, v66
	ds_read_b128 v[144:147], v66 offset:8192
	v_and_b32_e32 v87, 0xc0, v87
	v_and_b32_e32 v153, 0x100, v67
	s_waitcnt lgkmcnt(0)
	v_mfma_f32_32x32x16_bf16 v[68:83], v[148:151], v[140:143], v[68:83]
	ds_read_b128 v[140:143], v66
	v_or_b32_e32 v66, 0xa0, v200
	v_bitop3_b32 v66, v66, v193, v201 bitop3:0xde
	v_add_u32_e32 v66, 0, v66
	ds_read_b128 v[148:151], v66 offset:8192
	v_lshlrev_b32_e32 v86, 1, v86
	v_and_b32_e32 v152, 32, v86
	s_waitcnt lgkmcnt(0)
	v_mfma_f32_32x32x16_bf16 v[68:83], v[144:147], v[140:143], v[68:83]
	ds_read_b128 v[140:143], v66
	v_or_b32_e32 v66, 0xc0, v200
	v_bitop3_b32 v66, v66, v193, v201 bitop3:0xde
	v_add_u32_e32 v66, 0, v66
	ds_read_b128 v[144:147], v66 offset:8192
	v_lshlrev_b32_e32 v86, 2, v192
	v_cmp_le_u32_e32 vcc, v86, v84
	s_waitcnt lgkmcnt(0)
	v_mfma_f32_32x32x16_bf16 v[68:83], v[148:151], v[140:143], v[68:83]
	ds_read_b128 v[140:143], v66
	v_or_b32_e32 v148, 0xe0, v200
	v_and_or_b32 v66, v67, 24, v87
	v_bitop3_b32 v67, v148, v193, v201 bitop3:0xde
	v_add_u32_e32 v67, 0, v67
	ds_read_b128 v[148:151], v67 offset:8192
	v_or3_b32 v204, v66, v152, v153
	s_waitcnt lgkmcnt(0)
	v_mfma_f32_32x32x16_bf16 v[68:83], v[144:147], v[140:143], v[68:83]
	ds_read_b128 v[140:143], v67
	v_or_b32_e32 v191, 2, v86
	v_or_b32_e32 v190, 3, v86
	v_or_b32_e32 v189, 8, v86
	v_or_b32_e32 v188, 9, v86
	v_or_b32_e32 v187, 10, v86
	v_lshlrev_b32_e32 v203, 3, v192
	s_waitcnt lgkmcnt(0)
	v_mfma_f32_32x32x16_bf16 v[68:83], v[148:151], v[140:143], v[68:83]
	v_add_u32_e32 v205, 0, v193
	v_or_b32_e32 v186, 11, v86
	v_or_b32_e32 v185, 16, v86
	v_or_b32_e32 v184, 17, v86
	v_or_b32_e32 v183, 18, v86
	v_or_b32_e32 v182, 19, v86
	v_or_b32_e32 v181, 24, v86
	s_nop 4
	v_cvt_pk_bf16_f32 v66, v68, s0
	v_cndmask_b32_e32 v66, 0, v66, vcc
	v_cvt_pk_bf16_f32 v67, v69, s0
	v_cmp_lt_u32_e32 vcc, v86, v84
	v_add3_u32 v69, v205, v201, v203
	ds_read2_b64 v[142:145], v69 offset1:16
	v_cndmask_b32_e32 v67, 0, v67, vcc
	v_perm_b32 v152, v67, v66, s45
	v_cvt_pk_bf16_f32 v66, v70, s0
	v_cmp_le_u32_e32 vcc, v191, v84
	v_cvt_pk_bf16_f32 v67, v71, s0
	v_or_b32_e32 v70, 16, v203
	v_cndmask_b32_e32 v66, 0, v66, vcc
	v_cmp_le_u32_e32 vcc, v190, v84
	v_xad_u32 v70, v70, v201, v205
	s_waitcnt lgkmcnt(0)
	v_mov_b32_e32 v71, v143
	v_cndmask_b32_e32 v67, 0, v67, vcc
	v_perm_b32 v153, v67, v66, s45
	v_cvt_pk_bf16_f32 v66, v72, s0
	v_cmp_le_u32_e32 vcc, v189, v84
	v_cvt_pk_bf16_f32 v67, v73, s0
	ds_read_b64 v[72:73], v70
	v_cndmask_b32_e32 v66, 0, v66, vcc
	v_cmp_le_u32_e32 vcc, v188, v84
	v_mov_b32_e32 v70, v142
	v_cvt_pk_bf16_f32 v68, v54, v55
	v_cndmask_b32_e32 v67, 0, v67, vcc
	v_perm_b32 v154, v67, v66, s45
	v_cvt_pk_bf16_f32 v66, v74, s0
	v_cmp_le_u32_e32 vcc, v187, v84
	v_cvt_pk_bf16_f32 v67, v75, s0
	v_or_b32_e32 v74, 32, v203
	v_cndmask_b32_e32 v66, 0, v66, vcc
	v_cmp_le_u32_e32 vcc, v186, v84
	v_or_b32_e32 v75, 48, v203
	v_cvt_pk_bf16_f32 v69, v56, v57
	v_cndmask_b32_e32 v67, 0, v67, vcc
	v_perm_b32 v155, v67, v66, s45
	v_cvt_pk_bf16_f32 v66, v76, s0
	v_cmp_le_u32_e32 vcc, v185, v84
	v_cvt_pk_bf16_f32 v67, v77, s0
	v_or_b32_e32 v76, 64, v203
	v_cndmask_b32_e32 v66, 0, v66, vcc
	v_cmp_le_u32_e32 vcc, v184, v84
	v_xad_u32 v74, v74, v201, v205
	v_xad_u32 v75, v75, v201, v205
	v_cndmask_b32_e32 v67, 0, v67, vcc
	v_perm_b32 v140, v67, v66, s45
	v_cvt_pk_bf16_f32 v66, v78, s0
	v_cmp_le_u32_e32 vcc, v183, v84
	v_cvt_pk_bf16_f32 v67, v79, s0
	v_xad_u32 v76, v76, v201, v205
	v_cndmask_b32_e32 v66, 0, v66, vcc
	v_cmp_le_u32_e32 vcc, v182, v84
	v_cvt_pk_bf16_f32 v151, v81, s0
	ds_read_b64 v[146:147], v74
	ds_read_b64 v[148:149], v75
	ds_read_b64 v[192:193], v76
	v_cndmask_b32_e32 v67, 0, v67, vcc
	v_perm_b32 v141, v67, v66, s45
	v_cvt_pk_bf16_f32 v66, v80, s0
	v_cmp_le_u32_e32 vcc, v181, v84
	v_cvt_pk_bf16_f32 v67, v52, v53
	v_or_b32_e32 v143, 0x50, v203
	v_cndmask_b32_e32 v150, 0, v66, vcc
	v_cvt_pk_bf16_f32 v66, v50, v51
	v_cvt_pk_bf16_f32 v195, v60, v61
	v_cvt_pk_bf16_f32 v196, v62, v63
	s_waitcnt lgkmcnt(0)
	v_mfma_f32_32x32x16_bf16 v[66:81], v[70:73], v[66:69], 0
	v_cvt_pk_bf16_f32 v197, v64, v65
	v_xad_u32 v143, v143, v201, v205
	v_or_b32_e32 v167, 25, v86
	v_cmp_le_u32_e32 vcc, v167, v84
	v_or_b32_e32 v163, 26, v86
	v_or_b32_e32 v87, 27, v86
	v_cndmask_b32_e32 v142, 0, v151, vcc
	v_mfma_f32_32x32x16_bf16 v[66:81], v[146:149], v[194:197], v[66:81]
	ds_read_b64 v[194:195], v143
	v_cvt_pk_bf16_f32 v146, v34, v35
	v_cvt_pk_bf16_f32 v147, v36, v37
	v_cvt_pk_bf16_f32 v148, v38, v39
	v_cvt_pk_bf16_f32 v149, v40, v41
	v_perm_b32 v142, v142, v150, s45
	v_or_b32_e32 v143, 0x60, v203
	s_waitcnt lgkmcnt(0)
	v_mfma_f32_32x32x16_bf16 v[66:81], v[192:195], v[146:149], v[66:81]
	v_or_b32_e32 v150, 0x70, v203
	v_or_b32_e32 v151, 0x90, v203
	v_xad_u32 v143, v143, v201, v205
	v_xad_u32 v150, v150, v201, v205
	v_xad_u32 v151, v151, v201, v205
	ds_read_b64 v[196:197], v143
	ds_read_b64 v[198:199], v150
	ds_read_b64 v[150:151], v151
	v_cvt_pk_bf16_f32 v146, v42, v43
	v_cvt_pk_bf16_f32 v147, v44, v45
	v_cvt_pk_bf16_f32 v148, v46, v47
	v_cvt_pk_bf16_f32 v149, v48, v49
	v_or_b32_e32 v143, 0xa0, v203
	v_xad_u32 v143, v143, v201, v205
	s_waitcnt lgkmcnt(0)
	v_mfma_f32_32x32x16_bf16 v[66:81], v[196:199], v[146:149], v[66:81]
	v_mov_b32_e32 v148, v144
	v_mov_b32_e32 v149, v145
	v_cvt_pk_bf16_f32 v144, v18, v19
	v_cvt_pk_bf16_f32 v145, v20, v21
	v_cvt_pk_bf16_f32 v146, v22, v23
	v_cvt_pk_bf16_f32 v147, v24, v25
	v_or_b32_e32 v192, 0xd0, v203
	v_xad_u32 v194, v192, v201, v205
	v_mfma_f32_32x32x16_bf16 v[66:81], v[148:151], v[144:147], v[66:81]
	v_or_b32_e32 v146, 0xb0, v203
	v_xad_u32 v146, v146, v201, v205
	ds_read_b64 v[148:149], v143
	ds_read_b64 v[150:151], v146
	v_cvt_pk_bf16_f32 v144, v26, v27
	v_cvt_pk_bf16_f32 v145, v28, v29
	v_cvt_pk_bf16_f32 v146, v30, v31
	v_cvt_pk_bf16_f32 v147, v32, v33
	v_or_b32_e32 v143, 0xc0, v203
	v_xad_u32 v143, v143, v201, v205
	s_waitcnt lgkmcnt(0)
	v_mfma_f32_32x32x16_bf16 v[66:81], v[148:151], v[144:147], v[66:81]
	ds_read_b64 v[192:193], v143
	ds_read_b64 v[194:195], v194
	v_cvt_pk_bf16_f32 v82, v82, s0
	v_cmp_le_u32_e32 vcc, v163, v84
	v_cvt_pk_bf16_f32 v83, v83, s0
	v_cvt_pk_bf16_f32 v144, v2, v3
	v_cndmask_b32_e32 v82, 0, v82, vcc
	v_cmp_le_u32_e32 vcc, v87, v84
	v_cvt_pk_bf16_f32 v145, v4, v5
	v_cvt_pk_bf16_f32 v146, v6, v7
	v_cvt_pk_bf16_f32 v147, v8, v9
	v_cndmask_b32_e32 v83, 0, v83, vcc
	v_perm_b32 v143, v83, v82, s45
	s_waitcnt lgkmcnt(0)
	v_mfma_f32_32x32x16_bf16 v[66:81], v[192:195], v[144:147], v[66:81]
	v_or_b32_e32 v82, 0xe0, v203
	v_xad_u32 v82, v82, v201, v205
	v_or_b32_e32 v83, 0xf0, v203
	v_xad_u32 v83, v83, v201, v205
	ds_read_b64 v[144:145], v82
	ds_read_b64 v[146:147], v83
	v_cvt_pk_bf16_f32 v148, v10, v11
	v_cvt_pk_bf16_f32 v149, v12, v13
	v_cvt_pk_bf16_f32 v150, v14, v15
	v_cvt_pk_bf16_f32 v151, v16, v17
	v_add_u32_e32 v202, s7, v204
	v_permlane32_swap_b32_e32 v152, v154
	s_waitcnt lgkmcnt(0)
	v_mfma_f32_32x32x16_bf16 v[66:81], v[144:147], v[148:151], v[66:81]
	ds_read_b64_tr_b16 v[144:145], v202 offset:0
	ds_read_b64_tr_b16 v[146:147], v202 offset:0x800
	ds_read_b64_tr_b16 v[148:149], v202 offset:0x1000
	ds_read_b64_tr_b16 v[150:151], v202 offset:0x1800
	s_waitcnt lgkmcnt(0)
	v_permlane32_swap_b32_e32 v153, v155
	v_permlane32_swap_b32_e32 v140, v142
	v_permlane32_swap_b32_e32 v141, v143
	v_add_u32_e32 v82, 0, v200
	v_add_u32_e32 v83, 0x14200, v82
	v_mfma_f32_32x32x16_bf16 v[66:81], v[152:155], v[144:147], v[66:81]
	ds_read_b128 v[152:155], v83
	v_add_u32_e32 v83, 0x14220, v82
	ds_read_b128 v[192:195], v83
	v_add_u32_e32 v83, 0x14240, v82
	ds_read_b128 v[196:199], v83
	v_add_u32_e32 v83, 0x14260, v82
	s_add_i32 s51, 0, 0x4000
	ds_read_b128 v[200:203], v83
	s_waitcnt lgkmcnt(0)
	v_pk_mul_f32 v[50:51], v[50:51], v[152:153]
	v_add_u32_e32 v83, s51, v204
	ds_read_b64_tr_b16 v[152:153], v83 offset:0
	v_pk_mul_f32 v[52:53], v[52:53], v[154:155]
	ds_read_b64_tr_b16 v[154:155], v83 offset:0x800
	v_pk_mul_f32 v[54:55], v[54:55], v[192:193]
	ds_read_b64_tr_b16 v[192:193], v83 offset:0x1000
	v_pk_mul_f32 v[56:57], v[56:57], v[194:195]
	ds_read_b64_tr_b16 v[194:195], v83 offset:0x1800
	s_waitcnt lgkmcnt(0)
	v_pk_mul_f32 v[62:63], v[62:63], v[200:201]
	v_pk_mul_f32 v[58:59], v[58:59], v[196:197]
	v_pk_mul_f32 v[64:65], v[64:65], v[202:203]
	v_pk_mul_f32 v[60:61], v[60:61], v[198:199]
	s_nop 1
	v_mfma_f32_32x32x16_bf16 v[50:65], v[152:155], v[144:147], v[50:65]
	v_add_u32_e32 v152, 0x14280, v82
	ds_read_b128 v[152:155], v152
	v_add_u32_e32 v196, 0x142c0, v82
	v_add_u32_e32 v200, 0x142e0, v82
	ds_read_b128 v[196:199], v196
	ds_read_b128 v[200:203], v200
	s_waitcnt lgkmcnt(0)
	v_pk_mul_f32 v[42:43], v[42:43], v[196:197]
	v_mfma_f32_32x32x16_bf16 v[50:65], v[192:195], v[148:151], v[50:65]
	v_add_u32_e32 v192, 0x142a0, v82
	ds_read_b128 v[192:195], v192
	v_mul_f32_e64 v34, v34, v152
	v_mul_f32_e64 v35, v35, v153
	ds_read_b64_tr_b16 v[152:153], v83 offset:0x200
	v_mul_f32_e64 v36, v36, v154
	v_mul_f32_e64 v37, v37, v155
	ds_read_b64_tr_b16 v[154:155], v83 offset:0xa00
	s_waitcnt lgkmcnt(0)
	v_pk_mul_f32 v[38:39], v[38:39], v[192:193]
	ds_read_b64_tr_b16 v[192:193], v83 offset:0x1200
	v_pk_mul_f32 v[40:41], v[40:41], v[194:195]
	ds_read_b64_tr_b16 v[194:195], v83 offset:0x1a00
	s_waitcnt lgkmcnt(0)
	v_pk_mul_f32 v[46:47], v[46:47], v[200:201]
	v_pk_mul_f32 v[48:49], v[48:49], v[202:203]
	v_pk_mul_f32 v[44:45], v[44:45], v[198:199]
	s_nop 1
	v_mfma_f32_32x32x16_bf16 v[34:49], v[152:155], v[144:147], v[34:49]
	v_add_u32_e32 v152, 0x14300, v82
	ds_read_b128 v[152:155], v152
	v_add_u32_e32 v196, 0x14340, v82
	v_add_u32_e32 v200, 0x14360, v82
	ds_read_b128 v[196:199], v196
	ds_read_b128 v[200:203], v200
	s_waitcnt lgkmcnt(0)
	v_pk_mul_f32 v[26:27], v[26:27], v[196:197]
	v_mfma_f32_32x32x16_bf16 v[34:49], v[192:195], v[148:151], v[34:49]
	v_add_u32_e32 v192, 0x14320, v82
	ds_read_b128 v[192:195], v192
	v_mul_f32_e64 v18, v18, v152
	v_mul_f32_e64 v19, v19, v153
	ds_read_b64_tr_b16 v[152:153], v83 offset:0x400
	v_mul_f32_e64 v20, v20, v154
	v_mul_f32_e64 v21, v21, v155
	ds_read_b64_tr_b16 v[154:155], v83 offset:0xc00
	s_waitcnt lgkmcnt(0)
	v_pk_mul_f32 v[22:23], v[22:23], v[192:193]
	ds_read_b64_tr_b16 v[192:193], v83 offset:0x1400
	v_pk_mul_f32 v[24:25], v[24:25], v[194:195]
	ds_read_b64_tr_b16 v[194:195], v83 offset:0x1c00
	s_waitcnt lgkmcnt(0)
	v_pk_mul_f32 v[30:31], v[30:31], v[200:201]
	v_pk_mul_f32 v[32:33], v[32:33], v[202:203]
	v_pk_mul_f32 v[28:29], v[28:29], v[198:199]
	s_nop 1
	v_mfma_f32_32x32x16_bf16 v[18:33], v[152:155], v[144:147], v[18:33]
	v_add_u32_e32 v152, 0x14380, v82
	ds_read_b128 v[152:155], v152
	v_add_u32_e32 v196, 0x143c0, v82
	ds_read_b128 v[196:199], v196
	s_waitcnt lgkmcnt(0)
	v_pk_mul_f32 v[10:11], v[10:11], v[196:197]
	v_mfma_f32_32x32x16_bf16 v[18:33], v[192:195], v[148:151], v[18:33]
	v_add_u32_e32 v192, 0x143a0, v82
	v_add_u32_e32 v82, 0x143e0, v82
	ds_read_b128 v[192:195], v192
	ds_read_b128 v[200:203], v82
	v_mul_f32_e64 v2, v2, v152
	v_mul_f32_e64 v3, v3, v153
	v_pk_mul_f32 v[4:5], v[4:5], v[154:155]
	v_pk_mul_f32 v[12:13], v[12:13], v[198:199]
	v_mfma_f32_32x32x16_bf16 v[66:81], v[140:143], v[148:151], v[66:81]
	ds_read_b64_tr_b16 v[140:141], v83 offset:0x600
	ds_read_b64_tr_b16 v[142:143], v83 offset:0xe00
	ds_read_b64_tr_b16 v[152:153], v83 offset:0x1600
	ds_read_b64_tr_b16 v[154:155], v83 offset:0x1e00
	s_waitcnt lgkmcnt(0)
	s_waitcnt lgkmcnt(0)
	v_mul_f32_e64 v14, v14, v200
	v_mul_f32_e64 v15, v15, v201
	v_mul_f32_e64 v6, v6, v192
	v_mul_f32_e64 v7, v7, v193
	v_pk_mul_f32 v[16:17], v[16:17], v[202:203]
	v_pk_mul_f32 v[8:9], v[8:9], v[194:195]
	s_cmp_lg_u64 s[12:13], 0
	s_movk_i32 s100, 0x800
	s_cselect_b32 s100, s100, 0xfffff800
	s_cselect_b32 s101, 0, -1
	s_movk_i32 s98, 0x2800
	s_cselect_b32 s98, s98, 0xffffd800
	s_cselect_b32 s99, 0, -1
	s_and_b64 s[0:1], s[12:13], exec
	s_cselect_b32 s0, s49, s48
	v_lshlrev_b32_e32 v84, 1, v84
	s_lshl_b32 s0, s0, 5
	v_lshl_add_u64 v[82:83], s[28:29], 0, v[84:85]
	v_xor_b32_e32 v84, 31, v86
	s_add_i32 s0, s0, s47
	v_cndmask_b32_e64 v84, v84, v86, s[12:13]
	v_or_b32_e32 v84, s0, v84
	v_lshlrev_b32_e32 v84, 11, v84
	v_mfma_f32_32x32x16_bf16 v[2:17], v[140:143], v[144:147], v[2:17]
	v_cvt_pk_bf16_f32 v66, v66, s0
	v_lshl_add_u64 v[250:251], v[82:83], 0, v[84:85]
	global_store_short v[250:251], v66, off
	v_cvt_pk_bf16_f32 v140, v67, s0
	v_lshl_add_u64 v[250:251], v[250:251], 0, s[100:101]
	global_store_short v[250:251], v140, off
	v_cvt_pk_bf16_f32 v68, v68, s0
	v_lshl_add_u64 v[250:251], v[250:251], 0, s[100:101]
	global_store_short v[250:251], v68, off
	v_cvt_pk_bf16_f32 v68, v69, s0
	v_lshl_add_u64 v[250:251], v[250:251], 0, s[100:101]
	global_store_short v[250:251], v68, off
	v_cvt_pk_bf16_f32 v68, v70, s0
	v_lshl_add_u64 v[250:251], v[250:251], 0, s[98:99]
	global_store_short v[250:251], v68, off
	v_cvt_pk_bf16_f32 v68, v71, s0
	v_lshl_add_u64 v[250:251], v[250:251], 0, s[100:101]
	global_store_short v[250:251], v68, off
	v_cvt_pk_bf16_f32 v68, v72, s0
	v_lshl_add_u64 v[250:251], v[250:251], 0, s[100:101]
	global_store_short v[250:251], v68, off
	v_cvt_pk_bf16_f32 v68, v73, s0
	v_lshl_add_u64 v[250:251], v[250:251], 0, s[100:101]
	global_store_short v[250:251], v68, off
	v_cvt_pk_bf16_f32 v68, v74, s0
	v_lshl_add_u64 v[250:251], v[250:251], 0, s[98:99]
	global_store_short v[250:251], v68, off
	v_cvt_pk_bf16_f32 v68, v75, s0
	v_lshl_add_u64 v[250:251], v[250:251], 0, s[100:101]
	global_store_short v[250:251], v68, off
	v_cvt_pk_bf16_f32 v68, v76, s0
	v_lshl_add_u64 v[250:251], v[250:251], 0, s[100:101]
	global_store_short v[250:251], v68, off
	v_cvt_pk_bf16_f32 v68, v77, s0
	v_lshl_add_u64 v[250:251], v[250:251], 0, s[100:101]
	global_store_short v[250:251], v68, off
	v_cvt_pk_bf16_f32 v68, v78, s0
	v_lshl_add_u64 v[250:251], v[250:251], 0, s[98:99]
	global_store_short v[250:251], v68, off
	v_cvt_pk_bf16_f32 v68, v79, s0
	v_lshl_add_u64 v[250:251], v[250:251], 0, s[100:101]
	global_store_short v[250:251], v68, off
	v_mfma_f32_32x32x16_bf16 v[2:17], v[152:155], v[148:151], v[2:17]
	v_cvt_pk_bf16_f32 v68, v80, s0
	v_lshl_add_u64 v[250:251], v[250:251], 0, s[100:101]
	global_store_short v[250:251], v68, off
	v_cvt_pk_bf16_f32 v68, v81, s0
	v_mov_b32_e32 v82, v159
	s_and_b64 vcc, exec, s[8:9]
	v_lshl_add_u64 v[250:251], v[250:251], 0, s[100:101]
	global_store_short v[250:251], v68, off
	s_cbranch_vccnz .LBB0_981
	v_cvt_pk_bf16_f32 v66, v132, v133
	v_cvt_pk_bf16_f32 v67, v134, v135
	v_cvt_pk_bf16_f32 v68, v136, v137
	v_cvt_pk_bf16_f32 v69, v138, v139
	v_and_b32_e32 v87, 63, v82
	v_and_b32_e32 v83, 31, v82
	v_mfma_f32_32x32x16_bf16 v[66:81], v[66:69], v[128:131], 0
	s_nop 11
	v_add_f32_e32 v66, v180, v66
	v_mul_f32_e64 v84, |v66|, s40
	v_exp_f32_e32 v84, v84
	v_add_f32_e32 v67, v180, v67
	v_mul_f32_e64 v86, |v67|, s40
	v_exp_f32_e32 v86, v86
	v_add_f32_e32 v84, 1.0, v84
	v_cmp_gt_f32_e32 vcc, s41, v84
	v_min_f32_e32 v66, 0, v66
	v_add_f32_e32 v86, 1.0, v86
	v_cndmask_b32_e64 v140, 0, 32, vcc
	v_ldexp_f32 v84, v84, v140
	v_log_f32_e32 v84, v84
	v_cmp_gt_f32_e64 s[14:15], s41, v86
	v_cndmask_b32_e32 v140, 0, v179, vcc
	v_add_f32_e32 v68, v180, v68
	v_cndmask_b32_e64 v141, 0, 32, s[14:15]
	v_ldexp_f32 v86, v86, v141
	v_mul_f32_e32 v141, 0x3f317217, v84
	v_fma_f32 v141, v84, s42, -v141
	v_fmac_f32_e32 v141, 0x3377d1cf, v84
	v_log_f32_e32 v86, v86
	v_fmac_f32_e32 v141, 0x3f317217, v84
	v_cmp_lt_f32_e64 vcc, |v84|, s43
	s_nop 1
	v_cndmask_b32_e32 v84, v84, v141, vcc
	v_sub_f32_e32 v84, v84, v140
	v_sub_f32_e32 v66, v66, v84
	v_fma_f32 v84, v66, s44, 0
	v_min_f32_e32 v66, 0, v67
	v_mul_f32_e32 v67, 0x3f317217, v86
	v_mul_f32_e64 v140, |v68|, s40
	v_fma_f32 v67, v86, s42, -v67
	v_exp_f32_e32 v140, v140
	v_fmac_f32_e32 v67, 0x3377d1cf, v86
	v_fmac_f32_e32 v67, 0x3f317217, v86
	v_cmp_lt_f32_e64 vcc, |v86|, s43
	s_nop 1
	v_cndmask_b32_e32 v67, v86, v67, vcc
	v_cndmask_b32_e64 v86, 0, v179, s[14:15]
	v_sub_f32_e32 v67, v67, v86
	v_add_f32_e32 v86, 1.0, v140
	v_cmp_gt_f32_e32 vcc, s41, v86
	v_sub_f32_e32 v66, v66, v67
	s_nop 0
	v_cndmask_b32_e64 v140, 0, 32, vcc
	v_ldexp_f32 v86, v86, v140
	v_log_f32_e32 v86, v86
	v_fmamk_f32 v140, v66, 0x3d800000, v84
	v_min_f32_e32 v66, 0, v68
	v_add_f32_e32 v68, v180, v69
	v_mul_f32_e64 v69, |v68|, s40
	v_exp_f32_e32 v69, v69
	v_mul_f32_e32 v67, 0x3f317217, v86
	v_fma_f32 v67, v86, s42, -v67
	v_fmac_f32_e32 v67, 0x3377d1cf, v86
	v_fmac_f32_e32 v67, 0x3f317217, v86
	v_cmp_lt_f32_e64 s[14:15], |v86|, s43
	v_add_f32_e32 v69, 1.0, v69
	s_nop 0
	v_cndmask_b32_e64 v67, v86, v67, s[14:15]
	v_cndmask_b32_e32 v86, 0, v179, vcc
	v_cmp_gt_f32_e32 vcc, s41, v69
	v_sub_f32_e32 v67, v67, v86
	v_sub_f32_e32 v66, v66, v67
	v_cndmask_b32_e64 v86, 0, 32, vcc
	v_ldexp_f32 v69, v69, v86
	v_log_f32_e32 v69, v69
	v_fmamk_f32 v86, v66, 0x3d800000, v140
	v_min_f32_e32 v66, 0, v68
	v_add_f32_e32 v68, v180, v70
	v_mul_f32_e32 v67, 0x3f317217, v69
	v_mul_f32_e64 v70, |v68|, s40
	v_fma_f32 v67, v69, s42, -v67
	v_exp_f32_e32 v70, v70
	v_fmac_f32_e32 v67, 0x3377d1cf, v69
	v_fmac_f32_e32 v67, 0x3f317217, v69
	v_cmp_lt_f32_e64 s[14:15], |v69|, s43
	s_nop 1
	v_cndmask_b32_e64 v67, v69, v67, s[14:15]
	v_cndmask_b32_e32 v69, 0, v179, vcc
	v_sub_f32_e32 v67, v67, v69
	v_add_f32_e32 v69, 1.0, v70
	v_cmp_gt_f32_e32 vcc, s41, v69
	v_sub_f32_e32 v66, v66, v67
	v_min_f32_e32 v67, 0, v68
	v_cndmask_b32_e64 v70, 0, 32, vcc
	v_ldexp_f32 v69, v69, v70
	v_log_f32_e32 v69, v69
	v_add_f32_e32 v70, v180, v71
	v_mul_f32_e64 v71, |v70|, s40
	v_exp_f32_e32 v71, v71
	v_mul_f32_e32 v68, 0x3f317217, v69
	v_fma_f32 v68, v69, s42, -v68
	v_fmac_f32_e32 v68, 0x3377d1cf, v69
	v_fmac_f32_e32 v68, 0x3f317217, v69
	v_cmp_lt_f32_e64 s[14:15], |v69|, s43
	v_fmamk_f32 v66, v66, 0x3d800000, v86
	s_nop 0
	v_cndmask_b32_e64 v68, v69, v68, s[14:15]
	v_cndmask_b32_e32 v69, 0, v179, vcc
	v_sub_f32_e32 v68, v68, v69
	v_add_f32_e32 v69, 1.0, v71
	v_cmp_gt_f32_e32 vcc, s41, v69
	v_sub_f32_e32 v67, v67, v68
	v_fma_f32 v141, v67, s44, 0
	v_cndmask_b32_e64 v71, 0, 32, vcc
	v_ldexp_f32 v69, v69, v71
	v_log_f32_e32 v69, v69
	v_min_f32_e32 v67, 0, v70
	v_add_f32_e32 v70, v180, v72
	v_mul_f32_e64 v71, |v70|, s40
	v_mul_f32_e32 v68, 0x3f317217, v69
	v_fma_f32 v68, v69, s42, -v68
	v_exp_f32_e32 v71, v71
	v_fmac_f32_e32 v68, 0x3377d1cf, v69
	v_fmac_f32_e32 v68, 0x3f317217, v69
	v_cmp_lt_f32_e64 s[14:15], |v69|, s43
	s_nop 1
	v_cndmask_b32_e64 v68, v69, v68, s[14:15]
	v_cndmask_b32_e32 v69, 0, v179, vcc
	v_sub_f32_e32 v68, v68, v69
	v_add_f32_e32 v69, 1.0, v71
	v_cmp_gt_f32_e32 vcc, s41, v69
	v_sub_f32_e32 v67, v67, v68
	v_fmamk_f32 v142, v67, 0x3d800000, v141
	v_cndmask_b32_e64 v71, 0, 32, vcc
	v_ldexp_f32 v69, v69, v71
	v_log_f32_e32 v69, v69
	v_min_f32_e32 v67, 0, v70
	v_add_f32_e32 v70, v180, v73
	v_mul_f32_e64 v71, |v70|, s40
	v_mul_f32_e32 v68, 0x3f317217, v69
	v_fma_f32 v68, v69, s42, -v68
	v_exp_f32_e32 v71, v71
	v_fmac_f32_e32 v68, 0x3377d1cf, v69
	v_fmac_f32_e32 v68, 0x3f317217, v69
	v_cmp_lt_f32_e64 s[14:15], |v69|, s43
	s_nop 1
	v_cndmask_b32_e64 v68, v69, v68, s[14:15]
	v_cndmask_b32_e32 v69, 0, v179, vcc
	v_sub_f32_e32 v68, v68, v69
	v_add_f32_e32 v69, 1.0, v71
	v_cmp_gt_f32_e32 vcc, s41, v69
	v_sub_f32_e32 v67, v67, v68
	v_fmamk_f32 v143, v67, 0x3d800000, v142
	v_cndmask_b32_e64 v71, 0, 32, vcc
	v_ldexp_f32 v69, v69, v71
	v_log_f32_e32 v69, v69
	v_min_f32_e32 v67, 0, v70
	v_add_f32_e32 v70, v180, v74
	v_mul_f32_e64 v71, |v70|, s40
	v_mul_f32_e32 v68, 0x3f317217, v69
	v_fma_f32 v68, v69, s42, -v68
	v_exp_f32_e32 v71, v71
	v_fmac_f32_e32 v68, 0x3377d1cf, v69
	v_fmac_f32_e32 v68, 0x3f317217, v69
	v_cmp_lt_f32_e64 s[14:15], |v69|, s43
	s_nop 1
	v_cndmask_b32_e64 v68, v69, v68, s[14:15]
	v_cndmask_b32_e32 v69, 0, v179, vcc
	v_sub_f32_e32 v68, v68, v69
	v_add_f32_e32 v69, 1.0, v71
	v_cmp_gt_f32_e32 vcc, s41, v69
	v_sub_f32_e32 v67, v67, v68
	v_min_f32_e32 v68, 0, v70
	v_cndmask_b32_e64 v71, 0, 32, vcc
	v_ldexp_f32 v69, v69, v71
	v_log_f32_e32 v69, v69
	v_add_f32_e32 v71, v180, v75
	v_mul_f32_e64 v72, |v71|, s40
	v_exp_f32_e32 v72, v72
	v_mul_f32_e32 v70, 0x3f317217, v69
	v_fma_f32 v70, v69, s42, -v70
	v_fmac_f32_e32 v70, 0x3377d1cf, v69
	v_fmac_f32_e32 v70, 0x3f317217, v69
	v_cmp_lt_f32_e64 s[14:15], |v69|, s43
	v_fmamk_f32 v67, v67, 0x3d800000, v143
	s_nop 0
	v_cndmask_b32_e64 v69, v69, v70, s[14:15]
	v_cndmask_b32_e32 v70, 0, v179, vcc
	v_sub_f32_e32 v69, v69, v70
	v_add_f32_e32 v70, 1.0, v72
	v_cmp_gt_f32_e32 vcc, s41, v70
	v_sub_f32_e32 v68, v68, v69
	v_fma_f32 v75, v68, s44, 0
	v_cndmask_b32_e64 v72, 0, 32, vcc
	v_ldexp_f32 v70, v70, v72
	v_log_f32_e32 v70, v70
	v_min_f32_e32 v68, 0, v71
	v_add_f32_e32 v71, v180, v76
	v_mul_f32_e64 v72, |v71|, s40
	v_mul_f32_e32 v69, 0x3f317217, v70
	v_fma_f32 v69, v70, s42, -v69
	v_exp_f32_e32 v72, v72
	v_fmac_f32_e32 v69, 0x3377d1cf, v70
	v_fmac_f32_e32 v69, 0x3f317217, v70
	v_cmp_lt_f32_e64 s[14:15], |v70|, s43
	s_nop 1
	v_cndmask_b32_e64 v69, v70, v69, s[14:15]
	v_cndmask_b32_e32 v70, 0, v179, vcc
	v_sub_f32_e32 v69, v69, v70
	v_add_f32_e32 v70, 1.0, v72
	v_cmp_gt_f32_e32 vcc, s41, v70
	v_sub_f32_e32 v68, v68, v69
	v_fmamk_f32 v76, v68, 0x3d800000, v75
	v_cndmask_b32_e64 v72, 0, 32, vcc
	v_ldexp_f32 v70, v70, v72
	v_log_f32_e32 v70, v70
	v_min_f32_e32 v68, 0, v71
	v_add_f32_e32 v71, v180, v77
	v_mul_f32_e64 v72, |v71|, s40
	v_mul_f32_e32 v69, 0x3f317217, v70
	v_fma_f32 v69, v70, s42, -v69
	v_exp_f32_e32 v72, v72
	v_fmac_f32_e32 v69, 0x3377d1cf, v70
	v_fmac_f32_e32 v69, 0x3f317217, v70
	v_cmp_lt_f32_e64 s[14:15], |v70|, s43
	s_nop 1
	v_cndmask_b32_e64 v69, v70, v69, s[14:15]
	v_cndmask_b32_e32 v70, 0, v179, vcc
	v_sub_f32_e32 v69, v69, v70
	v_add_f32_e32 v70, 1.0, v72
	v_cmp_gt_f32_e32 vcc, s41, v70
	v_sub_f32_e32 v68, v68, v69
	v_fmamk_f32 v77, v68, 0x3d800000, v76
	v_cndmask_b32_e64 v72, 0, 32, vcc
	v_ldexp_f32 v70, v70, v72
	v_log_f32_e32 v70, v70
	v_min_f32_e32 v68, 0, v71
	v_add_f32_e32 v71, v180, v78
	v_mul_f32_e64 v72, |v71|, s40
	v_mul_f32_e32 v69, 0x3f317217, v70
	v_fma_f32 v69, v70, s42, -v69
	v_exp_f32_e32 v72, v72
	v_fmac_f32_e32 v69, 0x3377d1cf, v70
	v_fmac_f32_e32 v69, 0x3f317217, v70
	v_cmp_lt_f32_e64 s[14:15], |v70|, s43
	s_nop 1
	v_cndmask_b32_e64 v69, v70, v69, s[14:15]
	v_cndmask_b32_e32 v70, 0, v179, vcc
	v_sub_f32_e32 v69, v69, v70
	v_add_f32_e32 v70, 1.0, v72
	v_cmp_gt_f32_e32 vcc, s41, v70
	v_sub_f32_e32 v68, v68, v69
	v_min_f32_e32 v69, 0, v71
	v_cndmask_b32_e64 v72, 0, 32, vcc
	v_ldexp_f32 v70, v70, v72
	v_log_f32_e32 v70, v70
	v_add_f32_e32 v72, v180, v79
	v_mul_f32_e64 v73, |v72|, s40
	v_exp_f32_e32 v73, v73
	v_mul_f32_e32 v71, 0x3f317217, v70
	v_fma_f32 v71, v70, s42, -v71
	v_fmac_f32_e32 v71, 0x3377d1cf, v70
	v_fmac_f32_e32 v71, 0x3f317217, v70
	v_cmp_lt_f32_e64 s[14:15], |v70|, s43
	v_fmamk_f32 v68, v68, 0x3d800000, v77
	s_nop 0
	v_cndmask_b32_e64 v70, v70, v71, s[14:15]
	v_cndmask_b32_e32 v71, 0, v179, vcc
	v_sub_f32_e32 v70, v70, v71
	v_add_f32_e32 v71, 1.0, v73
	v_cmp_gt_f32_e32 vcc, s41, v71
	v_sub_f32_e32 v69, v69, v70
	v_fma_f32 v78, v69, s44, 0
	v_cndmask_b32_e64 v73, 0, 32, vcc
	v_ldexp_f32 v71, v71, v73
	v_log_f32_e32 v71, v71
	v_min_f32_e32 v69, 0, v72
	v_add_f32_e32 v72, v180, v80
	v_mul_f32_e64 v73, |v72|, s40
	v_mul_f32_e32 v70, 0x3f317217, v71
	v_fma_f32 v70, v71, s42, -v70
	v_exp_f32_e32 v73, v73
	v_fmac_f32_e32 v70, 0x3377d1cf, v71
	v_fmac_f32_e32 v70, 0x3f317217, v71
	v_cmp_lt_f32_e64 s[14:15], |v71|, s43
	s_nop 1
	v_cndmask_b32_e64 v70, v71, v70, s[14:15]
	v_cndmask_b32_e32 v71, 0, v179, vcc
	v_sub_f32_e32 v70, v70, v71
	v_add_f32_e32 v71, 1.0, v73
	v_cmp_gt_f32_e32 vcc, s41, v71
	v_sub_f32_e32 v69, v69, v70
	v_fmamk_f32 v79, v69, 0x3d800000, v78
	v_cndmask_b32_e64 v73, 0, 32, vcc
	v_ldexp_f32 v71, v71, v73
	v_log_f32_e32 v71, v71
	v_min_f32_e32 v69, 0, v72
	v_add_f32_e32 v72, v180, v81
	v_mul_f32_e64 v73, |v72|, s40
	v_mul_f32_e32 v70, 0x3f317217, v71
	v_fma_f32 v70, v71, s42, -v70
	v_exp_f32_e32 v73, v73
	v_fmac_f32_e32 v70, 0x3377d1cf, v71
	v_fmac_f32_e32 v70, 0x3f317217, v71
	v_cmp_lt_f32_e64 s[14:15], |v71|, s43
	s_nop 1
	v_cndmask_b32_e64 v70, v71, v70, s[14:15]
	v_cndmask_b32_e32 v71, 0, v179, vcc
	v_sub_f32_e32 v70, v70, v71
	v_add_f32_e32 v71, 1.0, v73
	v_cmp_gt_f32_e32 vcc, s41, v71
	v_sub_f32_e32 v69, v69, v70
	v_fmamk_f32 v80, v69, 0x3d800000, v79
	v_cndmask_b32_e64 v73, 0, 32, vcc
	v_ldexp_f32 v71, v71, v73
	v_log_f32_e32 v71, v71
	v_min_f32_e32 v69, 0, v72
	v_mov_b32_e32 v72, v67
	v_mov_b32_e32 v73, v68
	v_mul_f32_e32 v70, 0x3f317217, v71
	v_fma_f32 v70, v71, s42, -v70
	v_fmac_f32_e32 v70, 0x3377d1cf, v71
	v_fmac_f32_e32 v70, 0x3f317217, v71
	v_cmp_lt_f32_e64 s[14:15], |v71|, s43
	s_nop 1
	v_cndmask_b32_e64 v70, v71, v70, s[14:15]
	v_cndmask_b32_e32 v71, 0, v179, vcc
	v_sub_f32_e32 v70, v70, v71
	v_sub_f32_e32 v69, v69, v70
	v_mov_b32_e32 v70, v66
	v_mov_b32_e32 v71, v66
	s_nop 1
	v_permlane32_swap_b32_e32 v70, v71
	v_cmp_gt_u32_e32 vcc, 32, v87
	v_fmamk_f32 v69, v69, 0x3d800000, v80
	v_mov_b32_e32 v74, v69
	v_cndmask_b32_e32 v70, v70, v71, vcc
	v_mov_b32_e32 v71, v67
	s_nop 1
	v_permlane32_swap_b32_e32 v71, v72
	v_cndmask_b32_e32 v71, v71, v72, vcc
	v_mov_b32_e32 v72, v68
	s_nop 1
	v_permlane32_swap_b32_e32 v72, v73
	v_cndmask_b32_e32 v72, v72, v73, vcc
	v_mov_b32_e32 v73, v69
	s_nop 1
	v_permlane32_swap_b32_e32 v73, v74
	v_cndmask_b32_e32 v74, v73, v74, vcc
	v_lshlrev_b32_e32 v73, 6, v82
	v_cndmask_b32_e64 v81, v70, 0, vcc
	v_and_b32_e32 v82, 0x800, v73
	v_lshlrev_b32_e32 v73, 2, v83
	v_add_f32_e32 v83, v81, v84
	v_add3_u32 v82, s4, v73, v82
	v_add_f32_e32 v84, v81, v140
	ds_write2st64_b32 v82, v83, v84 offset1:2
	v_add_f32_e32 v83, v81, v86
	v_add_f32_e32 v84, v81, v66
	ds_write2st64_b32 v82, v83, v84 offset0:4 offset1:6
	v_cndmask_b32_e32 v83, v71, v70, vcc
	v_add_f32_e32 v83, v83, v66
	v_add_f32_e32 v81, v81, v83
	v_add_f32_e32 v83, v141, v81
	v_add_f32_e32 v84, v142, v81
	ds_write2st64_b32 v82, v83, v84 offset0:16 offset1:18
	v_add_f32_e32 v83, v143, v81
	v_add_f32_e32 v84, v67, v81
	ds_write2st64_b32 v82, v83, v84 offset0:20 offset1:22
	v_cndmask_b32_e32 v83, v72, v71, vcc
	v_add_f32_e32 v83, v83, v67
	v_add_f32_e32 v81, v83, v81
	v_add_f32_e32 v75, v75, v81
	v_add_f32_e32 v76, v76, v81
	ds_write2st64_b32 v82, v75, v76 offset0:32 offset1:34
	v_add_f32_e32 v75, v77, v81
	v_add_f32_e32 v76, v68, v81
	ds_write2st64_b32 v82, v75, v76 offset0:36 offset1:38
	v_cndmask_b32_e32 v75, v74, v72, vcc
	v_add_f32_e32 v75, v75, v68
	v_add_f32_e32 v75, v75, v81
	v_add_f32_e32 v76, v78, v75
	v_add_f32_e32 v77, v79, v75
	ds_write2st64_b32 v82, v76, v77 offset0:48 offset1:50
	v_add_f32_e32 v76, v80, v75
	v_add_f32_e32 v75, v69, v75
	ds_write2st64_b32 v82, v76, v75 offset0:52 offset1:54
	s_and_saveexec_b64 s[14:15], vcc
	s_cbranch_execz .LBB0_980
	v_add_f32_e32 v66, v66, v67
	v_add_f32_e32 v67, v68, v69
	v_add_f32_e32 v66, v66, v67
	v_add_f32_e32 v67, v70, v71
	v_add_f32_e32 v66, v67, v66
	v_add_f32_e32 v67, v72, v74
	v_add_f32_e32 v66, v67, v66
	v_mul_f32_e32 v67, 0x3fb8aa3b, v66
	v_exp_f32_e32 v67, v67
	v_add_u32_e32 v68, s5, v73
	ds_write_b32 v68, v66
	v_add_u32_e32 v66, s10, v73
	ds_write_b32 v66, v67
